# gdn_prep record stores through SGPR base + 32-bit offsets
# baseline (speedup 1.0000x reference)
; DI unsigned pk2(float lo, float hi) { f32x2 v = {lo, hi}; bf16x2_t r = __builtin_convertvector(v, bf16x2_t); return __builtin_bit_cast(unsigned, r); }
; DI int PERM(int p) { return (p & ~31) + 16 * ((p >> 2) & 1) + 4 * ((p >> 3) & 3) + (p & 3); }
; DI void phase_gdn_prep(const Params& p, int l, char* smem) {
;     ...
;         {
;             const int r = tid >> 2, part = tid & 3;
;             u32x4 v0, v1, w0, w1;
; #pragma unroll
;             for (int j = 0; j < 8; ++j) {
;                 const int p0 = part * 16 + 2 * j, p1 = p0 + 1;
;                 const unsigned a = pk2(sk[r * 65 + PERM(p0)], sk[r * 65 + PERM(p1)]);
;                 const unsigned c = pk2(sv[p0 * 65 + r], sv[p1 * 65 + r]);
;                 if (j < 4) { v0[j] = a; w0[j] = c; } else { v1[j - 4] = a; w1[j - 4] = c; }
;             }
;             *(u32x4*)(rec + (r * 64 + part * 16) * 2) = v0; *(u32x4*)(rec + (r * 64 + part * 16 + 8) * 2) = v1;
;             *(u32x4*)(rec + 32768 + (r * 64 + part * 16) * 2) = w0; *(u32x4*)(rec + 32768 + (r * 64 + part * 16 + 8) * 2) = w1;
;         }
;         __syncthreads();
.LBB0_263:
	s_add_u32 s4, s88, 0x8000
	s_addc_u32 s5, s89, 0
	s_andn2_b64 vcc, exec, s[90:91]
	s_mov_b32 s86, s30
	ds_read_b32 v76, v171 offset:33280
	v_add_u32_e32 v187, 0x8000, v172
	ds_read2_b32 v[200:201], v187 offset0:128 offset1:193
	ds_read2_b32 v[202:203], v179 offset0:64 offset1:80
	ds_read2_b32 v[204:205], v180 offset0:64 offset1:80
	v_add_u32_e32 v187, 0x8400, v172
	ds_read2_b32 v[206:207], v187 offset0:2 offset1:132
	ds_read2_b32 v[208:209], v181 offset0:64 offset1:80
	ds_read2_b32 v[230:231], v182 offset0:64 offset1:80
	ds_read_b32 v185, v171 offset:34320
	v_add_u32_e32 v187, 0x8600, v172
	ds_read2_b32 v[232:233], v187 offset0:69 offset1:134
	v_add_u32_e32 v187, 0x8800, v172
	ds_read2_b32 v[234:235], v187 offset0:71 offset1:136
	ds_read2_b32 v[236:237], v183 offset0:64 offset1:80
	ds_read2_b32 v[238:239], v184 offset0:64 offset1:80
	v_add_u32_e32 v187, 0x8a00, v172
	ds_read2_b32 v[240:241], v187 offset0:73 offset1:138
	ds_read_b32 v186, v158 offset:16640
	ds_read_b32 v188, v159 offset:16640
	v_add_u32_e32 v187, 0x8c00, v172
	ds_read2_b32 v[244:245], v187 offset0:75 offset1:140
	v_add_u32_e32 v187, 0x8e00, v172
	ds_read2_b32 v[254:255], v187 offset0:77 offset1:142
	ds_read_b32 v191, v160 offset:16704
	ds_read_b32 v243, v161 offset:16704
	s_waitcnt lgkmcnt(0)
	v_cvt_pk_bf16_f32 v36, v76, v200
	v_cvt_pk_bf16_f32 v58, v202, v204
	v_cvt_pk_bf16_f32 v60, v203, v205
	v_cvt_pk_bf16_f32 v37, v201, v206
	v_cvt_pk_bf16_f32 v59, v208, v230
	v_cvt_pk_bf16_f32 v38, v185, v207
	v_cvt_pk_bf16_f32 v61, v209, v231
	v_cvt_pk_bf16_f32 v39, v232, v233
	v_cvt_pk_bf16_f32 v192, v234, v235
	v_cvt_pk_bf16_f32 v196, v236, v238
	v_cvt_pk_bf16_f32 v193, v240, v241
	v_cvt_pk_bf16_f32 v197, v186, v188
	v_cvt_pk_bf16_f32 v194, v244, v245
	v_cvt_pk_bf16_f32 v198, v237, v239
	v_cvt_pk_bf16_f32 v195, v254, v255
	v_cvt_pk_bf16_f32 v199, v191, v243
	global_store_dwordx4 v42, v[58:61], s[88:89]
	global_store_dwordx4 v42, v[196:199], s[88:89] offset:16
	global_store_dwordx4 v42, v[36:39], s[4:5]
	global_store_dwordx4 v44, v[192:195], s[4:5]
	s_barrier
	s_cbranch_vccz .LBB0_347

; DI void phase_gdn_prep(const Params& p, int l, char* smem) {
;     ...
;         {
;             const int t = tid >> 2, part = tid & 3;
;             float s1 = 0.f, s2 = 0.f;
; #pragma unroll
;             for (int j = 0; j < 16; ++j) { const float a = sq[t * 65 + part * 16 + j], c = sk[t * 65 + part * 16 + j]; s1 += a * a; s2 += c * c; }
;             s1 += __shfl_xor(s1, 1); s1 += __shfl_xor(s1, 2); s2 += __shfl_xor(s2, 1); s2 += __shfl_xor(s2, 2);
;             const float r1 = rsqrtf(s1 + 1e-6f) * 0.125f, r2 = rsqrtf(s2 + 1e-6f);
; #pragma unroll
;             for (int j = 0; j < 16; ++j) { sq[t * 65 + part * 16 + j] *= r1; sk[t * 65 + part * 16 + j] *= r2; }
;         }
;         __syncthreads();
.LBB0_281:
	s_or_b64 exec, exec, s[88:89]
	v_add_u32_e32 v39, 0x4118, v118
	s_waitcnt lgkmcnt(0)
	s_barrier
	v_add_u32_e32 v59, 0x4100, v118
	v_add_u32_e32 v58, 0x4108, v118
	v_add_u32_e32 v38, 0x4110, v118
	ds_read2_b32 v[0:1], v118 offset1:1
	ds_read2_b32 v[2:3], v118 offset0:2 offset1:3
	ds_read2_b32 v[4:5], v118 offset0:4 offset1:5
	ds_read2_b32 v[6:7], v118 offset0:6 offset1:7
	ds_read2_b32 v[8:9], v39 offset1:1
	ds_read2_b32 v[10:11], v59 offset1:1
	ds_read2_b32 v[12:13], v58 offset1:1
	ds_read2_b32 v[14:15], v38 offset1:1
	s_waitcnt lgkmcnt(7)
	v_mov_b32_e32 v23, v1
	v_mov_b32_e32 v21, v0
	s_waitcnt lgkmcnt(2)
	v_mov_b32_e32 v22, v11
	v_mov_b32_e32 v20, v10
	v_pk_mul_f32 v[22:23], v[22:23], v[22:23]
	s_waitcnt lgkmcnt(1)
	v_mov_b32_e32 v24, v13
	v_pk_fma_f32 v[20:21], v[20:21], v[20:21], v[22:23]
	v_mov_b32_e32 v22, v12
	v_mov_b32_e32 v23, v2
	v_mov_b32_e32 v25, v3
	v_pk_fma_f32 v[20:21], v[22:23], v[22:23], v[20:21]
	s_waitcnt lgkmcnt(0)
	v_mov_b32_e32 v22, v14
	v_pk_fma_f32 v[20:21], v[24:25], v[24:25], v[20:21]
	v_mov_b32_e32 v23, v4
	v_pk_mul_f32 v[16:17], v[6:7], v[6:7]
	v_pk_mul_f32 v[18:19], v[8:9], v[8:9]
	v_mov_b32_e32 v24, v15
	v_mov_b32_e32 v25, v5
	v_pk_fma_f32 v[20:21], v[22:23], v[22:23], v[20:21]
	v_mov_b32_e32 v22, v18
	v_pk_fma_f32 v[20:21], v[24:25], v[24:25], v[20:21]
	v_mov_b32_e32 v23, v16
	v_pk_add_f32 v[20:21], v[20:21], v[22:23]
	v_mov_b32_e32 v16, v19
	v_add_u32_e32 v61, 0x4120, v118
	ds_read2_b32 v[18:19], v118 offset0:8 offset1:9
	v_pk_add_f32 v[16:17], v[20:21], v[16:17]
	ds_read2_b32 v[20:21], v118 offset0:10 offset1:11
	ds_read2_b32 v[22:23], v118 offset0:12 offset1:13
	ds_read2_b32 v[24:25], v118 offset0:14 offset1:15
	ds_read2_b32 v[28:29], v61 offset1:1
	v_add_u32_e32 v60, 0x4128, v118
	v_add_u32_e32 v37, 0x4130, v118
	v_add_u32_e32 v36, 0x4138, v118
	ds_read2_b32 v[30:31], v60 offset1:1
	ds_read2_b32 v[32:33], v37 offset1:1
	ds_read2_b32 v[34:35], v36 offset1:1
	s_waitcnt lgkmcnt(7)
	v_pk_mul_f32 v[26:27], v[18:19], v[18:19]
	s_waitcnt lgkmcnt(3)
	v_pk_mul_f32 v[186:187], v[28:29], v[28:29]
	v_mov_b32_e32 v205, v26
	v_mov_b32_e32 v204, v186
	v_pk_mul_f32 v[192:193], v[20:21], v[20:21]
	s_waitcnt lgkmcnt(2)
	v_pk_mul_f32 v[194:195], v[30:31], v[30:31]
	v_pk_add_f32 v[16:17], v[16:17], v[204:205]
	v_mov_b32_e32 v26, v187
	v_pk_add_f32 v[16:17], v[16:17], v[26:27]
	v_mov_b32_e32 v26, v194
	v_mov_b32_e32 v27, v192
	v_pk_mul_f32 v[196:197], v[22:23], v[22:23]
	s_waitcnt lgkmcnt(1)
	v_pk_mul_f32 v[198:199], v[32:33], v[32:33]
	v_pk_add_f32 v[16:17], v[16:17], v[26:27]
	v_mov_b32_e32 v192, v195
	v_pk_add_f32 v[16:17], v[16:17], v[192:193]
	v_mov_b32_e32 v26, v198
	v_mov_b32_e32 v27, v196
	v_pk_mul_f32 v[200:201], v[24:25], v[24:25]
	s_waitcnt lgkmcnt(0)
	v_pk_mul_f32 v[202:203], v[34:35], v[34:35]
	v_pk_add_f32 v[16:17], v[16:17], v[26:27]
	v_mov_b32_e32 v196, v199
	v_pk_add_f32 v[16:17], v[16:17], v[196:197]
	v_mov_b32_e32 v26, v202
	v_mov_b32_e32 v27, v200
	v_pk_add_f32 v[16:17], v[16:17], v[26:27]
	v_mov_b32_e32 v200, v203
	v_pk_add_f32 v[16:17], v[16:17], v[200:201]
	ds_bpermute_b32 v27, v65, v17
	ds_bpermute_b32 v26, v65, v16
	s_mov_b32 s4, 0x358637bd
	s_mov_b32 s2, 0x800000
	v_add_u32_e32 v185, v68, v69
	v_add_u32_e32 v186, v68, v70
	s_waitcnt lgkmcnt(0)
	v_pk_add_f32 v[16:17], v[16:17], v[26:27]
	ds_bpermute_b32 v27, v66, v17
	ds_bpermute_b32 v26, v66, v16
	v_readlane_b32 s52, v250, 51
	v_readlane_b32 s60, v250, 59
	v_readlane_b32 s61, v250, 60
	s_mov_b32 s78, 0x800000
	s_waitcnt lgkmcnt(0)
	v_pk_add_f32 v[16:17], v[16:17], v[26:27]
	v_readlane_b32 s53, v250, 52
	v_pk_add_f32 v[16:17], v[16:17], s[4:5] op_sel_hi:[1,0]
	s_mul_i32 s5, s86, 0xa000
	v_mul_f32_e32 v26, 0x4b800000, v17
	v_cmp_gt_f32_e32 vcc, s2, v17
	s_mul_hi_i32 s4, s86, 0xa000
	s_add_u32 s88, s60, s5
	v_cndmask_b32_e32 v17, v17, v26, vcc
	v_rsq_f32_e32 v17, v17
	s_addc_u32 s89, s61, s4
	s_add_u32 s4, s88, 0x2000
	s_addc_u32 s5, s89, 0
	v_mul_f32_e32 v26, 0x45800000, v17
	v_cndmask_b32_e32 v17, v17, v26, vcc
	v_mul_f32_e32 v26, 0x3e000000, v17
	v_pk_mul_f32 v[0:1], v[0:1], v[26:27] op_sel_hi:[1,0]
	ds_write2_b32 v118, v0, v1 offset1:1
	v_pk_mul_f32 v[0:1], v[2:3], v[26:27] op_sel_hi:[1,0]
	ds_write2_b32 v118, v0, v1 offset0:2 offset1:3
	v_pk_mul_f32 v[0:1], v[4:5], v[26:27] op_sel_hi:[1,0]
	v_mul_f32_e32 v2, 0x4b800000, v16
	v_cmp_gt_f32_e32 vcc, s2, v16
	ds_write2_b32 v118, v0, v1 offset0:4 offset1:5
	v_pk_mul_f32 v[0:1], v[6:7], v[26:27] op_sel_hi:[1,0]
	v_cndmask_b32_e32 v2, v16, v2, vcc
	ds_write2_b32 v118, v0, v1 offset0:6 offset1:7
	v_pk_mul_f32 v[0:1], v[18:19], v[26:27] op_sel_hi:[1,0]
	v_rsq_f32_e32 v2, v2
	ds_write2_b32 v118, v0, v1 offset0:8 offset1:9
	v_pk_mul_f32 v[0:1], v[20:21], v[26:27] op_sel_hi:[1,0]
	ds_write2_b32 v118, v0, v1 offset0:10 offset1:11
	v_pk_mul_f32 v[0:1], v[22:23], v[26:27] op_sel_hi:[1,0]
	ds_write2_b32 v118, v0, v1 offset0:12 offset1:13
	v_pk_mul_f32 v[0:1], v[24:25], v[26:27] op_sel_hi:[1,0]
	ds_write2_b32 v118, v0, v1 offset0:14 offset1:15
	v_mul_f32_e32 v0, 0x45800000, v2
	v_cndmask_b32_e32 v0, v2, v0, vcc
	v_pk_mul_f32 v[2:3], v[10:11], v[0:1] op_sel_hi:[1,0]
	ds_write2_b32 v59, v2, v3 offset1:1
	v_pk_mul_f32 v[2:3], v[12:13], v[0:1] op_sel_hi:[1,0]
	ds_write2_b32 v58, v2, v3 offset1:1
	v_pk_mul_f32 v[2:3], v[14:15], v[0:1] op_sel_hi:[1,0]
	ds_write2_b32 v38, v2, v3 offset1:1
	v_pk_mul_f32 v[2:3], v[8:9], v[0:1] op_sel_hi:[1,0]
	ds_write2_b32 v39, v2, v3 offset1:1
	v_pk_mul_f32 v[2:3], v[28:29], v[0:1] op_sel_hi:[1,0]
	ds_write2_b32 v61, v2, v3 offset1:1
	v_pk_mul_f32 v[2:3], v[30:31], v[0:1] op_sel_hi:[1,0]
	ds_write2_b32 v60, v2, v3 offset1:1
	v_pk_mul_f32 v[2:3], v[32:33], v[0:1] op_sel_hi:[1,0]
	v_pk_mul_f32 v[0:1], v[34:35], v[0:1] op_sel_hi:[1,0]
	ds_write2_b32 v37, v2, v3 offset1:1
	ds_write2_b32 v36, v0, v1 offset1:1
	s_waitcnt lgkmcnt(0)
	s_barrier
; DI void phase_gdn_prep(const Params& p, int l, char* smem) {
;     ...
;             {
;                 const int t = tid >> 2, part = tid & 3, sw = (t >> 1) & 7;
;                 u32x4 a0, a1, c0, c1;
; #pragma unroll
;                 for (int j = 0; j < 4; ++j) {
;                     a0[j] = pk2(sq[t * 65 + part * 16 + 2 * j], sq[t * 65 + part * 16 + 2 * j + 1]); a1[j] = pk2(sq[t * 65 + part * 16 + 8 + 2 * j], sq[t * 65 + part * 16 + 9 + 2 * j]);
;                     c0[j] = pk2(sk[t * 65 + part * 16 + 2 * j], sk[t * 65 + part * 16 + 2 * j + 1]); c1[j] = pk2(sk[t * 65 + part * 16 + 8 + 2 * j], sk[t * 65 + part * 16 + 9 + 2 * j]);
;                 }
;                 *(u32x4*)(qb + t * 128 + (((part * 2) ^ sw) << 4)) = a0; *(u32x4*)(qb + t * 128 + (((part * 2 + 1) ^ sw) << 4)) = a1;
;                 *(u32x4*)(kb + t * 128 + (((part * 2) ^ sw) << 4)) = c0; *(u32x4*)(kb + t * 128 + (((part * 2 + 1) ^ sw) << 4)) = c1;
;             }
;             __syncthreads();
;             const int wv = tid >> 6, fr = lane & 15, fq = lane >> 4;
;             const int rc = wv * 16 + fr, swc = (rc >> 1) & 7;
;             bf16x8 kB[2], qB[2];
; #pragma unroll
;             for (int ks = 0; ks < 2; ++ks) {
;                 kB[ks] = *(const bf16x8*)(kb + rc * 128 + (((ks * 4 + fq) ^ swc) << 4));
;                 qB[ks] = *(const bf16x8*)(qb + rc * 128 + (((ks * 4 + fq) ^ swc) << 4));
;             }
; #pragma unroll
;             for (int st = 0; st < 4; ++st) {
;                 const int rs = st * 16 + fr, sws = (rs >> 1) & 7;
;                 const bf16x8 kA0 = *(const bf16x8*)(kb + rs * 128 + (((0 + fq) ^ sws) << 4)), kA1 = *(const bf16x8*)(kb + rs * 128 + (((4 + fq) ^ sws) << 4));
;                 f32x4 z = (f32x4){0.f, 0.f, 0.f, 0.f};
;                 kkt[st] = mfma(kA1, kB[1], mfma(kA0, kB[0], z));
;                 qkt[st] = mfma(kA1, qB[1], mfma(kA0, qB[0], z));
;             }
;         }
;         {
;             const int r = tid >> 2, part = tid & 3;
;             const float eg = __expf(sgc[r]);
;             u32x4 v0, v1, w0, w1;
; #pragma unroll
;             for (int j = 0; j < 8; ++j) {
;                 const int p0 = part * 16 + 2 * j, p1 = p0 + 1;
;                 const unsigned a = pk2(sq[r * 65 + PERM(p0)] * eg, sq[r * 65 + PERM(p1)] * eg);
;                 const int c0 = PERM(p0), c1 = PERM(p1);
	ds_read2_b32 v[0:1], v118 offset1:1
	ds_read2_b32 v[2:3], v118 offset0:8 offset1:9
	ds_read2_b32 v[6:7], v118 offset0:2 offset1:3
	ds_read2_b32 v[10:11], v118 offset0:4 offset1:5
	ds_read2_b32 v[16:17], v118 offset0:6 offset1:7
	ds_read2_b32 v[14:15], v118 offset0:10 offset1:11
	ds_read2_b32 v[18:19], v118 offset0:12 offset1:13
	ds_read2_b32 v[20:21], v118 offset0:14 offset1:15
	s_waitcnt lgkmcnt(6)
	v_cvt_pk_bf16_f32 v4, v2, v3
	ds_read2_b32 v[2:3], v59 offset1:1
	ds_read2_b32 v[12:13], v61 offset1:1
	ds_read2_b32 v[22:23], v58 offset1:1
	ds_read2_b32 v[24:25], v38 offset1:1
	ds_read2_b32 v[26:27], v39 offset1:1
	s_waitcnt lgkmcnt(4)
	v_cvt_pk_bf16_f32 v8, v2, v3
	ds_read2_b32 v[2:3], v60 offset1:1
	ds_read2_b32 v[28:29], v37 offset1:1
	ds_read2_b32 v[30:31], v36 offset1:1
	v_cvt_pk_bf16_f32 v0, v0, v1
	s_waitcnt lgkmcnt(6)
	v_cvt_pk_bf16_f32 v12, v12, v13
	v_cvt_pk_bf16_f32 v1, v6, v7
	s_waitcnt lgkmcnt(2)
	v_cvt_pk_bf16_f32 v13, v2, v3
	v_cvt_pk_bf16_f32 v2, v10, v11
	v_cvt_pk_bf16_f32 v3, v16, v17
	v_cvt_pk_bf16_f32 v5, v14, v15
	v_cvt_pk_bf16_f32 v9, v22, v23
	v_cvt_pk_bf16_f32 v6, v18, v19
	v_cvt_pk_bf16_f32 v10, v24, v25
	s_waitcnt lgkmcnt(1)
	v_cvt_pk_bf16_f32 v14, v28, v29
	v_cvt_pk_bf16_f32 v7, v20, v21
	v_cvt_pk_bf16_f32 v11, v26, v27
	s_waitcnt lgkmcnt(0)
	v_cvt_pk_bf16_f32 v15, v30, v31
	ds_write_b128 v163, v[0:3] offset:49920
	ds_write_b128 v164, v[4:7] offset:49920
	ds_write_b128 v163, v[8:11] offset:58112
	ds_write_b128 v164, v[12:15] offset:58112
	s_waitcnt lgkmcnt(0)
	s_barrier
	ds_read_b128 v[0:3], v185 offset:58112
	v_add_u32_e32 v4, v67, v69
	ds_read_b128 v[192:195], v4 offset:58112
	ds_read_b128 v[196:199], v4 offset:49920
	ds_read_b128 v[4:7], v186 offset:58112
	ds_read_b128 v[8:11], v185 offset:60160
	v_add_u32_e32 v16, v67, v70
	s_waitcnt lgkmcnt(3)
	v_mfma_f32_16x16x32_bf16 v[12:15], v[0:3], v[192:195], 0
	ds_read_b128 v[200:203], v16 offset:58112
	ds_read_b128 v[28:31], v16 offset:49920
	ds_read_b128 v[32:35], v186 offset:60160
	v_readlane_b32 s2, v249, 25
	v_readlane_b32 s54, v250, 53
	s_waitcnt lgkmcnt(5)
	v_mfma_f32_16x16x32_bf16 v[0:3], v[0:3], v[196:199], 0
	v_readlane_b32 s55, v250, 54
	v_readlane_b32 s56, v250, 55
	v_readlane_b32 s57, v250, 56
	s_waitcnt lgkmcnt(1)
	v_mfma_f32_16x16x32_bf16 v[20:23], v[4:7], v[28:31], v[0:3]
	v_readlane_b32 s58, v250, 57
	v_readlane_b32 s59, v250, 58
	v_readlane_b32 s62, v250, 61
	v_mfma_f32_16x16x32_bf16 v[0:3], v[8:11], v[192:195], 0
	v_readlane_b32 s63, v250, 62
	v_readlane_b32 s64, v250, 63
	v_readlane_b32 s65, v249, 0
	s_waitcnt lgkmcnt(0)
	v_mfma_f32_16x16x32_bf16 v[16:19], v[32:35], v[200:203], v[0:3]
	v_readlane_b32 s66, v249, 1
	v_readlane_b32 s67, v249, 2
	v_mfma_f32_16x16x32_bf16 v[0:3], v[8:11], v[196:199], 0
	v_mfma_f32_16x16x32_bf16 v[24:27], v[4:7], v[200:203], v[12:15]
	v_mfma_f32_16x16x32_bf16 v[12:15], v[32:35], v[28:31], v[0:3]
	s_nop 5
	ds_read_b128 v[0:3], v185 offset:62208
	ds_read_b128 v[204:207], v185 offset:64256
	ds_read_b128 v[8:11], v186 offset:62208
	ds_read_b128 v[32:35], v186 offset:64256
	v_mov_b32_e32 v185, s2
	s_waitcnt lgkmcnt(3)
	v_mfma_f32_16x16x32_bf16 v[4:7], v[0:3], v[192:195], 0
	v_mfma_f32_16x16x32_bf16 v[0:3], v[0:3], v[196:199], 0
	s_waitcnt lgkmcnt(1)
	v_mfma_f32_16x16x32_bf16 v[4:7], v[8:11], v[200:203], v[4:7]
	v_mfma_f32_16x16x32_bf16 v[8:11], v[8:11], v[28:31], v[0:3]
	v_mfma_f32_16x16x32_bf16 v[0:3], v[204:207], v[192:195], 0
	s_waitcnt lgkmcnt(0)
	v_mfma_f32_16x16x32_bf16 v[0:3], v[32:35], v[200:203], v[0:3]
	ds_read2_b32 v[186:187], v174 offset0:64 offset1:129
	ds_read_b32 v188, v71
	ds_read_b64 v[192:193], v119
	ds_read2_b32 v[200:201], v120 offset1:1
	ds_read_b64 v[202:203], v121
	ds_read_b32 v185, v185
	ds_read_b32 v208, v165 offset:16640
	ds_read_b32 v209, v166 offset:16640
	ds_read_b32 v230, v167 offset:16640
	ds_read_b32 v231, v168 offset:16640
	ds_read_b32 v232, v169 offset:16640
	ds_read_b32 v233, v170 offset:16640
	s_waitcnt lgkmcnt(6)
	v_sub_f32_e32 v191, v185, v192
	v_mul_f32_e32 v191, 0x3fb8aa3b, v191
	v_exp_f32_e32 v234, v191
	v_sub_f32_e32 v191, v185, v193
	v_mul_f32_e32 v191, 0x3fb8aa3b, v191
	v_exp_f32_e32 v235, v191
	v_sub_f32_e32 v191, v185, v202
	v_mul_f32_e32 v191, 0x3fb8aa3b, v191
	v_mul_f32_e32 v188, 0x3fb8aa3b, v188
	v_exp_f32_e32 v202, v191
	v_sub_f32_e32 v191, v185, v203
	v_mfma_f32_16x16x32_bf16 v[192:195], v[204:207], v[196:199], 0
	v_exp_f32_e32 v188, v188
	ds_read2_b32 v[198:199], v175 offset0:64 offset1:129
	v_mul_f32_e32 v191, 0x3fb8aa3b, v191
	v_exp_f32_e32 v203, v191
	v_pk_mul_f32 v[186:187], v[186:187], v[234:235]
	v_mfma_f32_16x16x32_bf16 v[28:31], v[32:35], v[28:31], v[192:195]
	v_cvt_pk_bf16_f32 v196, v186, v187
	v_pk_mul_f32 v[186:187], v[188:189], v[200:201] op_sel_hi:[0,1]
	v_cvt_pk_bf16_f32 v200, v186, v187
	s_waitcnt lgkmcnt(0)
	v_pk_mul_f32 v[186:187], v[198:199], v[202:203]
	ds_read2_b32 v[198:199], v122 offset1:1
	ds_read_b32 v191, v123
	ds_read_b32 v197, v124
	ds_read_b32 v202, v125
	ds_read_b32 v203, v126
	ds_read_b32 v205, v127
	ds_read_b32 v234, v128
	ds_read_b32 v204, v129
	s_waitcnt lgkmcnt(6)
	v_sub_f32_e32 v191, v185, v191
	v_mul_f32_e32 v191, 0x3fb8aa3b, v191
	v_exp_f32_e32 v206, v191
	s_waitcnt lgkmcnt(5)
	v_sub_f32_e32 v191, v185, v197
	v_mul_f32_e32 v191, 0x3fb8aa3b, v191
	v_exp_f32_e32 v207, v191
	s_waitcnt lgkmcnt(2)
	v_sub_f32_e32 v191, v185, v205
	v_cvt_pk_bf16_f32 v197, v186, v187
	v_pk_mul_f32 v[186:187], v[188:189], v[198:199] op_sel_hi:[0,1]
	v_mul_f32_e32 v191, 0x3fb8aa3b, v191
	v_cvt_pk_bf16_f32 v201, v186, v187
	v_pk_mul_f32 v[186:187], v[208:209], v[206:207]
	v_exp_f32_e32 v206, v191
	s_waitcnt lgkmcnt(1)
; DI unsigned pk2(float lo, float hi) { f32x2 v = {lo, hi}; bf16x2_t r = __builtin_convertvector(v, bf16x2_t); return __builtin_bit_cast(unsigned, r); }
; DI void phase_gdn_prep(const Params& p, int l, char* smem) {
;     ...
;                 const unsigned c = pk2(sk[c0 * 65 + r] * __expf(sgc[63] - sgc[c0]), sk[c1 * 65 + r] * __expf(sgc[63] - sgc[c1]));
;                 if (j < 4) { v0[j] = a; w0[j] = c; } else { v1[j - 4] = a; w1[j - 4] = c; }
;             }
;             *(u32x4*)(rec + 8192 + (r * 64 + part * 16) * 2) = v0; *(u32x4*)(rec + 8192 + (r * 64 + part * 16 + 8) * 2) = v1;
;             *(u32x4*)(rec + 24576 + (r * 64 + part * 16) * 2) = w0; *(u32x4*)(rec + 24576 + (r * 64 + part * 16 + 8) * 2) = w1;
;         }
;         __syncthreads();
;         {
;             const int wv = tid >> 6, fr = lane & 15, fq = lane >> 4;
;             const int c = wv * 16 + fr;
;             const float gcc = sgc[c], bc = sbeta[c];
; #pragma unroll
;             for (int st = 0; st < 4; ++st) {
;                 const int s0 = st * 16 + fq * 4;
;                 f32x4 lv; float qv[4];
; #pragma unroll
;                 for (int ii = 0; ii < 4; ++ii) {
;                     const int s_ = s0 + ii;
;                     const float e = (s_ <= c) ? __expf(gcc - sgc[s_]) : 0.f;
;                     lv[ii] = (s_ < c) ? bc * kkt[st][ii] * e : 0.f;
;                     qv[ii] = qkt[st][ii] * e;
	v_sub_f32_e32 v191, v185, v234
	v_mul_f32_e32 v191, 0x3fb8aa3b, v191
	v_exp_f32_e32 v207, v191
	v_cvt_pk_bf16_f32 v198, v186, v187
	v_pk_mul_f32 v[186:187], v[188:189], v[202:203] op_sel_hi:[0,1]
	v_cvt_pk_bf16_f32 v202, v186, v187
	v_pk_mul_f32 v[186:187], v[230:231], v[206:207]
	ds_read_b64 v[206:207], v131
	ds_read2_b32 v[208:209], v176 offset0:64 offset1:129
	ds_read2_b32 v[230:231], v132 offset1:1
	ds_read_b64 v[234:235], v133
	ds_read_b32 v205, v130
	s_waitcnt lgkmcnt(4)
	v_sub_f32_e32 v191, v185, v206
	v_mul_f32_e32 v191, 0x3fb8aa3b, v191
	v_exp_f32_e32 v206, v191
	v_sub_f32_e32 v191, v185, v207
	v_mul_f32_e32 v191, 0x3fb8aa3b, v191
	v_exp_f32_e32 v207, v191
	s_waitcnt lgkmcnt(1)
	v_sub_f32_e32 v191, v185, v234
	v_cvt_pk_bf16_f32 v199, v186, v187
	s_waitcnt lgkmcnt(0)
	v_pk_mul_f32 v[186:187], v[188:189], v[204:205] op_sel_hi:[0,1]
	v_mul_f32_e32 v191, 0x3fb8aa3b, v191
	v_cvt_pk_bf16_f32 v203, v186, v187
	v_pk_mul_f32 v[186:187], v[208:209], v[206:207]
	v_exp_f32_e32 v208, v191
	v_sub_f32_e32 v191, v185, v235
	ds_read2_b32 v[206:207], v177 offset0:64 offset1:129
	v_mul_f32_e32 v191, 0x3fb8aa3b, v191
	v_exp_f32_e32 v209, v191
	v_cvt_pk_bf16_f32 v204, v186, v187
	v_pk_mul_f32 v[186:187], v[188:189], v[230:231] op_sel_hi:[0,1]
	v_cvt_pk_bf16_f32 v230, v186, v187
	s_waitcnt lgkmcnt(0)
	v_pk_mul_f32 v[186:187], v[206:207], v[208:209]
	v_mov_b32_e32 v34, 0
	v_cvt_pk_bf16_f32 v205, v186, v187
	ds_read_b32 v191, v135
	ds_read_b32 v209, v136
	ds_read_b32 v186, v137
	ds_read_b32 v187, v138
	ds_read2_b32 v[206:207], v134 offset1:1
	s_waitcnt lgkmcnt(4)
	v_sub_f32_e32 v191, v185, v191
	v_mul_f32_e32 v191, 0x3fb8aa3b, v191
	ds_read_b64 v[234:235], v139
	v_exp_f32_e32 v208, v191
	s_waitcnt lgkmcnt(4)
	v_sub_f32_e32 v191, v185, v209
	v_mul_f32_e32 v191, 0x3fb8aa3b, v191
	v_exp_f32_e32 v209, v191
	s_waitcnt lgkmcnt(0)
	v_sub_f32_e32 v191, v185, v234
	v_sub_f32_e32 v185, v185, v235
	v_pk_mul_f32 v[206:207], v[188:189], v[206:207] op_sel_hi:[0,1]
	v_mul_f32_e32 v191, 0x3fb8aa3b, v191
	v_mul_f32_e32 v185, 0x3fb8aa3b, v185
	v_cvt_pk_bf16_f32 v231, v206, v207
	v_pk_mul_f32 v[206:207], v[232:233], v[208:209]
	ds_read2_b32 v[208:209], v178 offset0:64 offset1:129
	ds_read2_b32 v[236:237], v140 offset0:16 offset1:17
	v_exp_f32_e32 v234, v191
	v_exp_f32_e32 v235, v185
	v_pk_mul_f32 v[186:187], v[188:189], v[186:187] op_sel_hi:[0,1]
	v_cvt_pk_bf16_f32 v232, v186, v187
	v_cvt_pk_bf16_f32 v206, v206, v207
	s_waitcnt lgkmcnt(1)
	v_pk_mul_f32 v[186:187], v[208:209], v[234:235]
	v_mov_b32_e32 v33, 0
	v_cvt_pk_bf16_f32 v207, v186, v187
	s_waitcnt lgkmcnt(0)
	v_pk_mul_f32 v[186:187], v[188:189], v[236:237] op_sel_hi:[0,1]
	v_cvt_pk_bf16_f32 v233, v186, v187
	global_store_dwordx4 v42, v[200:203], s[4:5]
	global_store_dwordx4 v44, v[230:233], s[4:5]
	s_add_u32 s4, s88, 0x6000
	s_addc_u32 s5, s89, 0
	global_store_dwordx4 v42, v[196:199], s[4:5]
	global_store_dwordx4 v44, v[204:207], s[4:5]
	s_barrier
	ds_read_b32 v186, v72
	ds_read_b32 v185, v73
	ds_read_b128 v[98:101], v141
	ds_read_b128 v[102:105], v141 offset:64
	ds_read_b128 v[106:109], v141 offset:128
	ds_read_b128 v[192:195], v141 offset:192
	v_lshrrev_b32_e32 v110, 6, v40
	v_and_b32_e32 v111, 15, v62
	v_lshl_or_b32 v110, v110, 4, v111
	v_lshrrev_b32_e32 v111, 4, v62
	v_lshlrev_b32_e32 v111, 2, v111
	v_sub_u32_e32 v110, v110, v111
	s_waitcnt lgkmcnt(0)
	v_sub_f32_e32 v81, v186, v98
	v_mul_f32_e32 v81, 0x3fb8aa3b, v81
	v_sub_f32_e32 v82, v186, v99
	v_mul_f32_e32 v82, 0x3fb8aa3b, v82
	v_sub_f32_e32 v83, v186, v100
	v_mul_f32_e32 v83, 0x3fb8aa3b, v83
	v_sub_f32_e32 v84, v186, v101
	v_mul_f32_e32 v84, 0x3fb8aa3b, v84
	v_sub_f32_e32 v85, v186, v102
	v_mul_f32_e32 v85, 0x3fb8aa3b, v85
	v_sub_f32_e32 v86, v186, v103
	v_mul_f32_e32 v86, 0x3fb8aa3b, v86
	v_sub_f32_e32 v87, v186, v104
	v_mul_f32_e32 v87, 0x3fb8aa3b, v87
	v_sub_f32_e32 v88, v186, v105
	v_mul_f32_e32 v88, 0x3fb8aa3b, v88
	v_sub_f32_e32 v89, v186, v106
	v_mul_f32_e32 v89, 0x3fb8aa3b, v89
	v_sub_f32_e32 v90, v186, v107
	v_mul_f32_e32 v90, 0x3fb8aa3b, v90
	v_sub_f32_e32 v91, v186, v108
	v_mul_f32_e32 v91, 0x3fb8aa3b, v91
	v_sub_f32_e32 v92, v186, v109
	v_mul_f32_e32 v92, 0x3fb8aa3b, v92
	v_sub_f32_e32 v93, v186, v192
	v_mul_f32_e32 v93, 0x3fb8aa3b, v93
	v_sub_f32_e32 v94, v186, v193
	v_mul_f32_e32 v94, 0x3fb8aa3b, v94
	v_sub_f32_e32 v95, v186, v194
	v_mul_f32_e32 v95, 0x3fb8aa3b, v95
	v_sub_f32_e32 v96, v186, v195
	v_mul_f32_e32 v96, 0x3fb8aa3b, v96
	v_exp_f32_e32 v81, v81
	v_exp_f32_e32 v82, v82
	v_exp_f32_e32 v83, v83
	v_exp_f32_e32 v84, v84
	v_exp_f32_e32 v85, v85
	v_exp_f32_e32 v86, v86
	v_exp_f32_e32 v87, v87
	v_exp_f32_e32 v88, v88
	v_exp_f32_e32 v89, v89
	v_exp_f32_e32 v90, v90
	v_exp_f32_e32 v91, v91
	v_exp_f32_e32 v92, v92
	v_exp_f32_e32 v93, v93
	v_exp_f32_e32 v94, v94
	v_exp_f32_e32 v95, v95
	v_exp_f32_e32 v96, v96
	v_cmp_le_i32_e64 vcc, 0, v110
	v_cmp_le_i32_e64 s[4:5], 1, v110
	v_cmp_le_i32_e64 s[6:7], 2, v110
	v_cndmask_b32_e64 v81, 0, v81, vcc
	v_cmp_le_i32_e64 vcc, 3, v110
	v_cndmask_b32_e64 v82, 0, v82, s[4:5]
	v_cmp_le_i32_e64 s[4:5], 16, v110
	v_cndmask_b32_e64 v83, 0, v83, s[6:7]
	v_cmp_le_i32_e64 s[6:7], 17, v110
	v_cndmask_b32_e64 v84, 0, v84, vcc
	v_cmp_le_i32_e64 vcc, 18, v110
	v_cndmask_b32_e64 v85, 0, v85, s[4:5]
	v_cmp_le_i32_e64 s[4:5], 19, v110
	v_cndmask_b32_e64 v86, 0, v86, s[6:7]
	v_cmp_le_i32_e64 s[6:7], 32, v110
	v_cndmask_b32_e64 v87, 0, v87, vcc
	v_cmp_le_i32_e64 vcc, 33, v110
	v_cndmask_b32_e64 v88, 0, v88, s[4:5]
	v_cmp_le_i32_e64 s[4:5], 34, v110
	v_cndmask_b32_e64 v89, 0, v89, s[6:7]
	v_cmp_le_i32_e64 s[6:7], 35, v110
	v_cndmask_b32_e64 v90, 0, v90, vcc
	v_cmp_le_i32_e64 vcc, 48, v110
	v_cndmask_b32_e64 v91, 0, v91, s[4:5]
	v_cmp_le_i32_e64 s[4:5], 49, v110
	v_cndmask_b32_e64 v92, 0, v92, s[6:7]
	v_cmp_le_i32_e64 s[6:7], 50, v110
	v_cndmask_b32_e64 v93, 0, v93, vcc
	v_cmp_le_i32_e64 vcc, 51, v110
	v_cndmask_b32_e64 v94, 0, v94, s[4:5]
	v_cndmask_b32_e64 v95, 0, v95, s[6:7]
	v_cndmask_b32_e64 v96, 0, v96, vcc

; DI unsigned pk2(float lo, float hi) { f32x2 v = {lo, hi}; bf16x2_t r = __builtin_convertvector(v, bf16x2_t); return __builtin_bit_cast(unsigned, r); }
; DI int PINV(int s) { return (s & ~31) | ((s & 12) << 1) | ((s & 16) >> 2) | (s & 3); }
; DI void phase_gdn_prep(const Params& p, int l, char* smem) {
;     ...
;             for (int st = 0; st < 4; ++st) {
;                 const int s0 = st * 16 + fq * 4;
;                 f32x4 lv; float qv[4];
; #pragma unroll
;                 for (int ii = 0; ii < 4; ++ii) {
;                     const int s_ = s0 + ii;
;                     const float e = (s_ <= c) ? __expf(gcc - sgc[s_]) : 0.f;
;                     lv[ii] = (s_ < c) ? bc * kkt[st][ii] * e : 0.f;
;                     qv[ii] = qkt[st][ii] * e;
;                 }
;                 *(f32x4*)(sL + c * 64 + s0) = lv;
;                 u32x2 o2; o2[0] = pk2(qv[0], qv[1]); o2[1] = pk2(qv[2], qv[3]);
;                 *(u32x2*)(rec + 16384 + (c * 64 + PINV(s0)) * 2) = o2;
.LBB0_289:
	v_mov_b32_e32 v187, v84
	s_waitcnt lgkmcnt(0)
	v_mul_f32_e32 v25, v25, v185
	v_readlane_b32 s4, v249, 50
	v_mul_f32_e32 v25, v25, v35
	v_readlane_b32 s5, v249, 51
	v_mul_f32_e32 v26, v26, v185
	v_mul_f32_e32 v26, v26, v34
	v_cndmask_b32_e64 v25, 0, v25, s[4:5]
	v_readlane_b32 s4, v249, 54
	v_readlane_b32 s5, v249, 55
	v_mul_f32_e32 v24, v24, v185
	v_mul_f32_e32 v34, v22, v34
	v_cndmask_b32_e64 v26, 0, v26, s[4:5]
	v_mul_f32_e32 v22, v27, v185
	v_readlane_b32 s4, v249, 58
	v_mul_f32_e32 v24, v24, v33
	v_mul_f32_e32 v20, v20, v33
	v_mul_f32_e32 v21, v21, v35
	v_mul_f32_e32 v22, v22, v187
	v_readlane_b32 s5, v249, 59
	v_cndmask_b32_e64 v24, 0, v24, s[10:11]
	v_mul_f32_e32 v23, v23, v187
	v_cndmask_b32_e64 v27, 0, v22, s[4:5]
	v_cvt_pk_bf16_f32 v22, v20, v21
	s_add_u32 s98, s88, 0x4000
	s_addc_u32 s99, s89, 0
	ds_write_b128 v145, v[24:27] offset:49920
	v_cvt_pk_bf16_f32 v23, v34, v23
	s_nop 0
	global_store_dwordx2 v56, v[22:23], s[98:99]

; DI unsigned pk2(float lo, float hi) { f32x2 v = {lo, hi}; bf16x2_t r = __builtin_convertvector(v, bf16x2_t); return __builtin_bit_cast(unsigned, r); }
; DI int PINV(int s) { return (s & ~31) | ((s & 12) << 1) | ((s & 16) >> 2) | (s & 3); }
; DI void phase_gdn_prep(const Params& p, int l, char* smem) {
;     ...
;             for (int st = 0; st < 4; ++st) {
;                 const int s0 = st * 16 + fq * 4;
;                 f32x4 lv; float qv[4];
; #pragma unroll
;                 for (int ii = 0; ii < 4; ++ii) {
;                     const int s_ = s0 + ii;
;                     const float e = (s_ <= c) ? __expf(gcc - sgc[s_]) : 0.f;
;                     lv[ii] = (s_ < c) ? bc * kkt[st][ii] * e : 0.f;
;                     qv[ii] = qkt[st][ii] * e;
;                 }
;                 *(f32x4*)(sL + c * 64 + s0) = lv;
;                 u32x2 o2; o2[0] = pk2(qv[0], qv[1]); o2[1] = pk2(qv[2], qv[3]);
;                 *(u32x2*)(rec + 16384 + (c * 64 + PINV(s0)) * 2) = o2;
.LBB0_297:
	v_mov_b32_e32 v25, v88
	s_mov_b64 s[4:5], 0x4000
	v_mul_f32_e32 v16, v16, v185
	v_readlane_b32 s4, v249, 62
	v_mul_f32_e32 v16, v16, v32
	v_readlane_b32 s5, v249, 63
	v_mul_f32_e32 v17, v17, v185
	v_mul_f32_e32 v17, v17, v23
	v_cndmask_b32_e64 v16, 0, v16, s[4:5]
	v_readlane_b32 s4, v248, 2
	v_readlane_b32 s5, v248, 3
	v_mul_f32_e32 v18, v18, v185
	v_mul_f32_e32 v18, v18, v24
	v_cndmask_b32_e64 v17, 0, v17, s[4:5]
	v_readlane_b32 s4, v248, 6
	v_readlane_b32 s5, v248, 7
	v_mul_f32_e32 v19, v19, v185
	v_mul_f32_e32 v14, v14, v24
	v_cndmask_b32_e64 v18, 0, v18, s[4:5]
	v_readlane_b32 s4, v248, 10
	v_mul_f32_e32 v12, v12, v32
	v_mul_f32_e32 v13, v13, v23
	v_mul_f32_e32 v19, v19, v25
	v_readlane_b32 s5, v248, 11
	v_mul_f32_e32 v15, v15, v25
	v_cvt_pk_bf16_f32 v12, v12, v13
	v_cndmask_b32_e64 v19, 0, v19, s[4:5]
	v_cvt_pk_bf16_f32 v13, v14, v15
	ds_write_b128 v145, v[16:19] offset:49984
	global_store_dwordx2 v56, v[12:13], s[98:99] offset:8

; DI unsigned pk2(float lo, float hi) { f32x2 v = {lo, hi}; bf16x2_t r = __builtin_convertvector(v, bf16x2_t); return __builtin_bit_cast(unsigned, r); }
; DI int PINV(int s) { return (s & ~31) | ((s & 12) << 1) | ((s & 16) >> 2) | (s & 3); }
; DI void phase_gdn_prep(const Params& p, int l, char* smem) {
;     ...
;             for (int st = 0; st < 4; ++st) {
;                 const int s0 = st * 16 + fq * 4;
;                 f32x4 lv; float qv[4];
; #pragma unroll
;                 for (int ii = 0; ii < 4; ++ii) {
;                     const int s_ = s0 + ii;
;                     const float e = (s_ <= c) ? __expf(gcc - sgc[s_]) : 0.f;
;                     lv[ii] = (s_ < c) ? bc * kkt[st][ii] * e : 0.f;
;                     qv[ii] = qkt[st][ii] * e;
;                 }
;                 *(f32x4*)(sL + c * 64 + s0) = lv;
;                 u32x2 o2; o2[0] = pk2(qv[0], qv[1]); o2[1] = pk2(qv[2], qv[3]);
;                 *(u32x2*)(rec + 16384 + (c * 64 + PINV(s0)) * 2) = o2;
.LBB0_305:
	v_mov_b32_e32 v15, v92
	v_mul_f32_e32 v4, v4, v185
	v_readlane_b32 s4, v248, 14
	v_mul_f32_e32 v4, v4, v22
	v_readlane_b32 s5, v248, 15
	v_mul_f32_e32 v5, v5, v185
	v_mul_f32_e32 v5, v5, v13
	v_cndmask_b32_e64 v4, 0, v4, s[4:5]
	v_readlane_b32 s4, v248, 18
	v_readlane_b32 s5, v248, 19
	v_mul_f32_e32 v6, v6, v185
	v_mul_f32_e32 v7, v7, v185
	v_cndmask_b32_e64 v5, 0, v5, s[4:5]
	v_readlane_b32 s4, v248, 22
	v_mul_f32_e32 v6, v6, v14
	v_readlane_b32 s5, v248, 23
	v_mul_f32_e32 v7, v7, v15
	v_mul_f32_e32 v10, v10, v14
	v_cndmask_b32_e64 v6, 0, v6, s[4:5]
	v_mul_f32_e32 v8, v8, v22
	v_mul_f32_e32 v9, v9, v13
	v_cndmask_b32_e64 v7, 0, v7, s[12:13]
	v_mul_f32_e32 v11, v11, v15
	ds_write_b128 v145, v[4:7] offset:50048
	v_cvt_pk_bf16_f32 v4, v8, v9
	v_cvt_pk_bf16_f32 v5, v10, v11
	global_store_dwordx2 v56, v[4:5], s[98:99] offset:64

; DI unsigned pk2(float lo, float hi) { f32x2 v = {lo, hi}; bf16x2_t r = __builtin_convertvector(v, bf16x2_t); return __builtin_bit_cast(unsigned, r); }
; DI int PINV(int s) { return (s & ~31) | ((s & 12) << 1) | ((s & 16) >> 2) | (s & 3); }
; DI void phase_gdn_prep(const Params& p, int l, char* smem) {
;     ...
;                 *(f32x4*)(sL + c * 64 + s0) = lv;
;                 u32x2 o2; o2[0] = pk2(qv[0], qv[1]); o2[1] = pk2(qv[2], qv[3]);
;                 *(u32x2*)(rec + 16384 + (c * 64 + PINV(s0)) * 2) = o2;
;             }
;         }
;         {
;             const int t = tid >> 2, part = tid & 3;
;             const float bt = sbeta[t], be = bt * __expf(sgc[t]);
; #pragma unroll
;             for (int j = 0; j < 16; ++j) { sv[t * 65 + part * 16 + j] *= bt; sk[t * 65 + part * 16 + j] *= be; }
;         }
;         __syncthreads();
;         { const int nxt = item + (int)gridDim.x; prefetch(nxt < 3072 ? nxt : item); }
.LBB0_313:
	v_mov_b32_e32 v6, v96
	v_mul_f32_e32 v0, v0, v185
	v_mul_f32_e32 v1, v1, v185
	v_mul_f32_e32 v2, v2, v185
	v_mul_f32_e32 v3, v3, v185
	v_mul_f32_e32 v0, v0, v12
	v_mul_f32_e32 v1, v1, v4
	v_mul_f32_e32 v2, v2, v5
	v_mul_f32_e32 v3, v3, v6
	v_cndmask_b32_e64 v0, 0, v0, s[16:17]
	v_cndmask_b32_e64 v1, 0, v1, s[20:21]
	v_cndmask_b32_e64 v2, 0, v2, s[24:25]
	v_mul_f32_e32 v5, v30, v5
	v_mul_f32_e32 v7, v28, v12
	v_mul_f32_e32 v4, v29, v4
	v_cndmask_b32_e64 v3, 0, v3, s[28:29]
	v_mul_f32_e32 v6, v31, v6
	ds_write_b128 v145, v[0:3] offset:50112
	v_cvt_pk_bf16_f32 v0, v7, v4
	v_cvt_pk_bf16_f32 v1, v5, v6
	global_store_dwordx2 v56, v[0:1], s[98:99] offset:72
	v_add_u32_e32 v1, 0x8200, v118
	ds_read_b32 v2, v74
	ds_read_b32 v0, v71
	ds_read2_b32 v[4:5], v1 offset0:0 offset1:1
	ds_read2_b32 v[6:7], v1 offset0:2 offset1:3
	ds_read2_b32 v[8:9], v1 offset0:4 offset1:5
	ds_read2_b32 v[10:11], v1 offset0:6 offset1:7
	ds_read2_b32 v[12:13], v1 offset0:8 offset1:9
	ds_read2_b32 v[14:15], v1 offset0:10 offset1:11
	ds_read2_b32 v[16:17], v1 offset0:12 offset1:13
	ds_read2_b32 v[18:19], v1 offset0:14 offset1:15
	v_readlane_b32 s4, v249, 16
	s_add_i32 s30, s86, s4
	s_cmpk_gt_i32 s30, 0xbff
	v_readlane_b32 s5, v249, 17
	s_cselect_b64 s[90:91], -1, 0
	s_cmpk_lt_i32 s30, 0xc00
	s_cselect_b32 s5, s30, s86
	s_ashr_i32 s6, s5, 8
	s_mul_hi_i32 s4, s6, 0x2aaaaaab
	s_lshr_b32 s7, s4, 31
	s_add_i32 s4, s4, s7
	s_mul_i32 s7, s4, 6
	s_lshl_b32 s5, s5, 6
	s_sub_i32 s86, s6, s7
	s_and_b32 s6, s5, 0x3fc0
	s_ashr_i32 s5, s4, 31
	s_sub_i32 s8, 2, s6
	s_lshl_b64 s[92:93], s[4:5], 14
	s_lshl_b32 s94, s86, 6
	v_cmp_lt_i32_e32 vcc, s8, v46
	s_or_b32 s92, s92, s6
	s_ashr_i32 s95, s94, 31
	s_and_b64 s[96:97], s[42:43], vcc
	s_waitcnt lgkmcnt(0)
	ds_read2_b32 v[20:21], v59 offset0:0 offset1:1
	ds_read2_b32 v[22:23], v59 offset0:2 offset1:3
	ds_read2_b32 v[24:25], v59 offset0:4 offset1:5
	ds_read2_b32 v[26:27], v59 offset0:6 offset1:7
	ds_read2_b32 v[28:29], v59 offset0:8 offset1:9
	ds_read2_b32 v[30:31], v59 offset0:10 offset1:11
	ds_read2_b32 v[32:33], v59 offset0:12 offset1:13
	ds_read2_b32 v[34:35], v59 offset0:14 offset1:15
	v_mul_f32_e32 v0, 0x3fb8aa3b, v0
	v_exp_f32_e32 v0, v0
	v_pk_mul_f32 v[4:5], v[2:3], v[4:5] op_sel_hi:[0,1]
	v_pk_mul_f32 v[6:7], v[2:3], v[6:7] op_sel_hi:[0,1]
	v_pk_mul_f32 v[8:9], v[2:3], v[8:9] op_sel_hi:[0,1]
	v_pk_mul_f32 v[10:11], v[2:3], v[10:11] op_sel_hi:[0,1]
	v_pk_mul_f32 v[12:13], v[2:3], v[12:13] op_sel_hi:[0,1]
	v_pk_mul_f32 v[14:15], v[2:3], v[14:15] op_sel_hi:[0,1]
	v_pk_mul_f32 v[16:17], v[2:3], v[16:17] op_sel_hi:[0,1]
	v_pk_mul_f32 v[18:19], v[2:3], v[18:19] op_sel_hi:[0,1]
	v_mul_f32_e32 v0, v2, v0
	s_waitcnt lgkmcnt(0)
	ds_write2_b32 v1, v4, v5 offset0:0 offset1:1
	ds_write2_b32 v1, v6, v7 offset0:2 offset1:3
	ds_write2_b32 v1, v8, v9 offset0:4 offset1:5
	ds_write2_b32 v1, v10, v11 offset0:6 offset1:7
	ds_write2_b32 v1, v12, v13 offset0:8 offset1:9
	ds_write2_b32 v1, v14, v15 offset0:10 offset1:11
	ds_write2_b32 v1, v16, v17 offset0:12 offset1:13
	ds_write2_b32 v1, v18, v19 offset0:14 offset1:15
	v_pk_mul_f32 v[20:21], v[0:1], v[20:21] op_sel_hi:[0,1]
	v_pk_mul_f32 v[22:23], v[0:1], v[22:23] op_sel_hi:[0,1]
	v_pk_mul_f32 v[24:25], v[0:1], v[24:25] op_sel_hi:[0,1]
	v_pk_mul_f32 v[26:27], v[0:1], v[26:27] op_sel_hi:[0,1]
	v_pk_mul_f32 v[28:29], v[0:1], v[28:29] op_sel_hi:[0,1]
	v_pk_mul_f32 v[30:31], v[0:1], v[30:31] op_sel_hi:[0,1]
	v_pk_mul_f32 v[32:33], v[0:1], v[32:33] op_sel_hi:[0,1]
	v_pk_mul_f32 v[34:35], v[0:1], v[34:35] op_sel_hi:[0,1]
	ds_write2_b32 v59, v20, v21 offset0:0 offset1:1
	ds_write2_b32 v59, v22, v23 offset0:2 offset1:3
	ds_write2_b32 v59, v24, v25 offset0:4 offset1:5
	ds_write2_b32 v59, v26, v27 offset0:6 offset1:7
	ds_write2_b32 v59, v28, v29 offset0:8 offset1:9
	ds_write2_b32 v59, v30, v31 offset0:10 offset1:11
	ds_write2_b32 v59, v32, v33 offset0:12 offset1:13
	ds_write2_b32 v59, v34, v35 offset0:14 offset1:15
	v_mov_b32_e32 v24, 0
	v_mov_b32_e32 v25, 0
	v_mov_b32_e32 v26, 0
	v_mov_b32_e32 v27, 0
	s_waitcnt lgkmcnt(0)
	s_barrier
	s_and_saveexec_b64 s[4:5], s[38:39]
	s_cbranch_execz .Lpbb_skip
	v_readlane_b32 s52, v250, 51
	v_lshl_add_u64 v[36:37], s[92:93], 0, v[40:41]
	v_readlane_b32 s64, v250, 63
	v_readlane_b32 s65, v249, 0
	s_ashr_i32 s87, s86, 31
	v_readlane_b32 s53, v250, 52
	v_add_u32_e32 v36, s92, v40
	v_mul_u32_u24_e32 v36, 48, v36
	s_lshl_b32 s2, s86, 2
	s_nop 1
	v_add_u32_e32 v36, s2, v36
	global_load_dword v55, v36, s[64:65]
	global_load_dword v49, v36, s[64:65] offset:24
	v_readlane_b32 s54, v250, 53
	v_readlane_b32 s55, v250, 54
	v_readlane_b32 s56, v250, 55
	v_readlane_b32 s57, v250, 56
	v_readlane_b32 s58, v250, 57
	v_readlane_b32 s59, v250, 58
	v_readlane_b32 s60, v250, 59
	v_readlane_b32 s61, v250, 60
	v_readlane_b32 s62, v250, 61
	v_readlane_b32 s63, v250, 62
	v_readlane_b32 s66, v249, 1
	v_readlane_b32 s67, v249, 2
